# phase-0 transpose item: all 32 tile loads in flight (distinct dead VGPRs) behind one counted vmcnt ladder instead of 4 serialized groups of 8
# speedup vs baseline: 1.0003x; 1.0003x over previous
.LBB0_62:
	s_mul_i32 s14, s14, s96
	s_sub_i32 s14, s38, s14
	s_lshl_b32 s14, s14, 6
	s_and_b32 s88, s14, 0xffc0
	v_lshlrev_b32_e32 v56, 2, v4
	v_or_b32_e32 v6, s88, v78
	v_or_b32_e32 v8, s88, v91
	v_or_b32_e32 v10, s88, v84
	v_or_b32_e32 v12, s88, v92
	v_or_b32_e32 v14, s88, v86
	v_or_b32_e32 v16, s88, v93
	v_or_b32_e32 v18, s88, v88
	v_add_u32_e32 v20, s88, v94
	v_lshl_add_u64 v[4:5], s[82:83], 0, v[56:57]
	v_mul_hi_u32_u24_e32 v7, s84, v6
	v_mul_u32_u24_e32 v6, s84, v6
	v_mul_hi_u32_u24_e32 v9, s84, v8
	v_mul_u32_u24_e32 v8, s84, v8
	v_mul_hi_u32_u24_e32 v11, s84, v10
	v_mul_u32_u24_e32 v10, s84, v10
	v_mul_hi_u32_u24_e32 v13, s84, v12
	v_mul_u32_u24_e32 v12, s84, v12
	v_mul_hi_u32_u24_e32 v15, s84, v14
	v_mul_u32_u24_e32 v14, s84, v14
	v_mul_hi_u32_u24_e32 v17, s84, v16
	v_mul_u32_u24_e32 v16, s84, v16
	v_mul_hi_u32_u24_e32 v19, s84, v18
	v_mul_u32_u24_e32 v18, s84, v18
	v_mul_hi_u32_u24_e32 v21, s84, v20
	v_mul_u32_u24_e32 v20, s84, v20
	v_lshl_add_u64 v[6:7], v[6:7], 2, v[4:5]
	v_lshl_add_u64 v[8:9], v[8:9], 2, v[4:5]
	v_lshl_add_u64 v[10:11], v[10:11], 2, v[4:5]
	v_lshl_add_u64 v[12:13], v[12:13], 2, v[4:5]
	v_lshl_add_u64 v[14:15], v[14:15], 2, v[4:5]
	v_lshl_add_u64 v[16:17], v[16:17], 2, v[4:5]
	v_lshl_add_u64 v[18:19], v[18:19], 2, v[4:5]
	v_lshl_add_u64 v[4:5], v[20:21], 2, v[4:5]
	global_load_dword v224, v[6:7], off
	s_nop 0
	global_load_dword v225, v[8:9], off
	s_nop 0
	global_load_dword v226, v[10:11], off
	global_load_dword v227, v[12:13], off
	s_nop 0
	global_load_dword v228, v[14:15], off
	global_load_dword v229, v[16:17], off
	global_load_dword v230, v[18:19], off
	s_nop 0
	global_load_dword v231, v[4:5], off
	s_add_i32 s14, s38, 1
	s_and_b32 s15, s14, 0xffff
	v_cvt_f32_u32_e32 v5, s15
	v_mul_f32_e32 v13, v5, v3
	v_trunc_f32_e32 v13, v13
	v_cvt_u32_f32_e32 v14, v13
	v_fma_f32 v5, -v13, v2, v5
	v_cmp_ge_f32_e64 s[60:61], |v5|, v2
	s_cmp_lg_u64 s[60:61], 0
	v_readfirstlane_b32 s15, v14
	s_addc_u32 s15, s15, 0
	s_and_b32 s60, s15, 0xffff
	s_lshl_b32 s89, s60, 6
	s_cmp_lt_u32 s60, 20
	s_cselect_b64 s[86:87], -1, 0
	s_and_b64 vcc, exec, s[6:7]
	v_or_b32_e32 v4, s89, v69
	s_cbranch_vccnz .LBB0_64
	s_bfe_i32 s61, s60, 0x10001
	s_lshl_b32 s60, s60, 5
	s_and_b32 s61, s61, 0xb00
	s_and_b32 s60, s60, 0xfff80
	s_add_i32 s61, s61, s60
	v_and_b32_e32 v4, 0x7f, v4
	v_or_b32_e32 v4, s61, v4
	s_branch .LBB0_65

.LBB0_65:
	s_mul_i32 s15, s15, s96
	s_sub_i32 s14, s14, s15
	s_lshl_b32 s14, s14, 6
	s_and_b32 s97, s14, 0xffc0
	v_lshlrev_b32_e32 v56, 2, v4
	v_or_b32_e32 v6, s97, v78
	v_or_b32_e32 v8, s97, v91
	v_or_b32_e32 v10, s97, v84
	v_or_b32_e32 v12, s97, v92
	v_or_b32_e32 v14, s97, v86
	v_or_b32_e32 v16, s97, v93
	v_or_b32_e32 v18, s97, v88
	v_add_u32_e32 v20, s97, v94
	v_lshl_add_u64 v[4:5], s[82:83], 0, v[56:57]
	v_mul_hi_u32_u24_e32 v7, s84, v6
	v_mul_u32_u24_e32 v6, s84, v6
	v_mul_hi_u32_u24_e32 v9, s84, v8
	v_mul_u32_u24_e32 v8, s84, v8
	v_mul_hi_u32_u24_e32 v11, s84, v10
	v_mul_u32_u24_e32 v10, s84, v10
	v_mul_hi_u32_u24_e32 v13, s84, v12
	v_mul_u32_u24_e32 v12, s84, v12
	v_mul_hi_u32_u24_e32 v15, s84, v14
	v_mul_u32_u24_e32 v14, s84, v14
	v_mul_hi_u32_u24_e32 v17, s84, v16
	v_mul_u32_u24_e32 v16, s84, v16
	v_mul_hi_u32_u24_e32 v19, s84, v18
	v_mul_u32_u24_e32 v18, s84, v18
	v_mul_hi_u32_u24_e32 v21, s84, v20
	v_mul_u32_u24_e32 v20, s84, v20
	v_lshl_add_u64 v[6:7], v[6:7], 2, v[4:5]
	v_lshl_add_u64 v[8:9], v[8:9], 2, v[4:5]
	v_lshl_add_u64 v[10:11], v[10:11], 2, v[4:5]
	v_lshl_add_u64 v[12:13], v[12:13], 2, v[4:5]
	v_lshl_add_u64 v[14:15], v[14:15], 2, v[4:5]
	v_lshl_add_u64 v[16:17], v[16:17], 2, v[4:5]
	v_lshl_add_u64 v[18:19], v[18:19], 2, v[4:5]
	v_lshl_add_u64 v[4:5], v[20:21], 2, v[4:5]
	global_load_dword v232, v[6:7], off
	s_nop 0
	global_load_dword v233, v[8:9], off
	s_nop 0
	global_load_dword v234, v[10:11], off
	global_load_dword v235, v[12:13], off
	s_nop 0
	global_load_dword v236, v[14:15], off
	global_load_dword v237, v[16:17], off
	global_load_dword v238, v[18:19], off
	s_nop 0
	global_load_dword v239, v[4:5], off
	s_add_i32 s14, s38, 2
	s_and_b32 s15, s14, 0xffff
	v_cvt_f32_u32_e32 v5, s15
	v_mul_f32_e32 v13, v5, v3
	v_trunc_f32_e32 v13, v13
	v_cvt_u32_f32_e32 v14, v13
	v_fma_f32 v5, -v13, v2, v5
	v_cmp_ge_f32_e64 s[60:61], |v5|, v2
	s_cmp_lg_u64 s[60:61], 0
	v_readfirstlane_b32 s15, v14
	s_addc_u32 s15, s15, 0
	s_and_b32 s61, s15, 0xffff
	s_lshl_b32 s60, s61, 6
	s_cmp_lt_u32 s61, 20
	s_cselect_b64 s[86:87], -1, 0
	s_and_b64 vcc, exec, s[6:7]
	v_or_b32_e32 v4, s60, v69
	s_cbranch_vccnz .LBB0_67
	s_bfe_i32 s70, s61, 0x10001
	s_lshl_b32 s61, s61, 5
	s_and_b32 s70, s70, 0xb00
	s_and_b32 s61, s61, 0xfff80
	s_add_i32 s70, s70, s61
	v_and_b32_e32 v4, 0x7f, v4
	v_or_b32_e32 v4, s70, v4
	s_branch .LBB0_68

.LBB0_68:
	s_mul_i32 s15, s15, s96
	s_sub_i32 s14, s14, s15
	s_lshl_b32 s14, s14, 6
	s_and_b32 s61, s14, 0xffc0
	v_lshlrev_b32_e32 v56, 2, v4
	v_or_b32_e32 v6, s61, v78
	v_or_b32_e32 v8, s61, v91
	v_or_b32_e32 v10, s61, v84
	v_or_b32_e32 v12, s61, v92
	v_or_b32_e32 v14, s61, v86
	v_or_b32_e32 v16, s61, v93
	v_or_b32_e32 v18, s61, v88
	v_add_u32_e32 v20, s61, v94
	v_lshl_add_u64 v[4:5], s[82:83], 0, v[56:57]
	v_mul_hi_u32_u24_e32 v7, s84, v6
	v_mul_u32_u24_e32 v6, s84, v6
	v_mul_hi_u32_u24_e32 v9, s84, v8
	v_mul_u32_u24_e32 v8, s84, v8
	v_mul_hi_u32_u24_e32 v11, s84, v10
	v_mul_u32_u24_e32 v10, s84, v10
	v_mul_hi_u32_u24_e32 v13, s84, v12
	v_mul_u32_u24_e32 v12, s84, v12
	v_mul_hi_u32_u24_e32 v15, s84, v14
	v_mul_u32_u24_e32 v14, s84, v14
	v_mul_hi_u32_u24_e32 v17, s84, v16
	v_mul_u32_u24_e32 v16, s84, v16
	v_mul_hi_u32_u24_e32 v19, s84, v18
	v_mul_u32_u24_e32 v18, s84, v18
	v_mul_hi_u32_u24_e32 v21, s84, v20
	v_mul_u32_u24_e32 v20, s84, v20
	v_lshl_add_u64 v[6:7], v[6:7], 2, v[4:5]
	v_lshl_add_u64 v[8:9], v[8:9], 2, v[4:5]
	v_lshl_add_u64 v[10:11], v[10:11], 2, v[4:5]
	v_lshl_add_u64 v[12:13], v[12:13], 2, v[4:5]
	v_lshl_add_u64 v[14:15], v[14:15], 2, v[4:5]
	v_lshl_add_u64 v[16:17], v[16:17], 2, v[4:5]
	v_lshl_add_u64 v[18:19], v[18:19], 2, v[4:5]
	v_lshl_add_u64 v[4:5], v[20:21], 2, v[4:5]
	global_load_dword v240, v[6:7], off
	s_nop 0
	global_load_dword v241, v[8:9], off
	s_nop 0
	global_load_dword v242, v[10:11], off
	global_load_dword v243, v[12:13], off
	s_nop 0
	global_load_dword v244, v[14:15], off
	global_load_dword v245, v[16:17], off
	global_load_dword v246, v[18:19], off
	s_nop 0
	global_load_dword v247, v[4:5], off
	s_add_i32 s15, s38, 3
	s_and_b32 s14, s15, 0xffff
	v_cvt_f32_u32_e32 v5, s14
	v_mul_f32_e32 v3, v5, v3
	v_trunc_f32_e32 v3, v3
	v_cvt_u32_f32_e32 v13, v3
	v_fma_f32 v3, -v3, v2, v5
	v_cmp_ge_f32_e64 s[70:71], |v3|, v2
	s_cmp_lg_u64 s[70:71], 0
	v_readfirstlane_b32 s14, v13
	s_addc_u32 s38, s14, 0
	s_and_b32 s70, s38, 0xffff
	s_lshl_b32 s14, s70, 6
	s_cmp_lt_u32 s70, 20
	s_cselect_b64 s[86:87], -1, 0
	s_and_b64 vcc, exec, s[6:7]
	v_or_b32_e32 v2, s14, v69
	s_cbranch_vccnz .LBB0_70
	s_bfe_i32 s6, s70, 0x10001
	s_lshl_b32 s7, s70, 5
	s_and_b32 s6, s6, 0xb00
	s_and_b32 s7, s7, 0xfff80
	s_add_i32 s6, s6, s7
	v_and_b32_e32 v2, 0x7f, v2
	v_or_b32_e32 v2, s6, v2
	s_branch .LBB0_71

.LBB0_71:
	s_mul_i32 s38, s38, s96
	s_sub_i32 s6, s15, s38
	s_lshl_b32 s6, s6, 6
	s_and_b32 s6, s6, 0xffc0
	v_lshlrev_b32_e32 v56, 2, v2
	v_or_b32_e32 v4, s6, v78
	v_or_b32_e32 v6, s6, v91
	v_or_b32_e32 v8, s6, v84
	v_or_b32_e32 v14, s6, v93
	v_or_b32_e32 v16, s6, v88
	v_lshl_add_u64 v[2:3], s[82:83], 0, v[56:57]
	v_mul_hi_u32_u24_e32 v5, s84, v4
	v_mul_u32_u24_e32 v4, s84, v4
	v_mul_hi_u32_u24_e32 v7, s84, v6
	v_mul_u32_u24_e32 v6, s84, v6
	v_mul_hi_u32_u24_e32 v9, s84, v8
	v_mul_u32_u24_e32 v8, s84, v8
	v_or_b32_e32 v10, s6, v92
	v_or_b32_e32 v12, s6, v86
	v_mul_hi_u32_u24_e32 v15, s84, v14
	v_mul_u32_u24_e32 v14, s84, v14
	v_mul_hi_u32_u24_e32 v17, s84, v16
	v_mul_u32_u24_e32 v16, s84, v16
	v_add_u32_e32 v18, s6, v94
	v_lshl_add_u64 v[4:5], v[4:5], 2, v[2:3]
	v_lshl_add_u64 v[6:7], v[6:7], 2, v[2:3]
	v_lshl_add_u64 v[8:9], v[8:9], 2, v[2:3]
	v_mul_hi_u32_u24_e32 v11, s84, v10
	v_mul_u32_u24_e32 v10, s84, v10
	v_mul_hi_u32_u24_e32 v13, s84, v12
	v_mul_u32_u24_e32 v12, s84, v12
	v_lshl_add_u64 v[14:15], v[14:15], 2, v[2:3]
	v_lshl_add_u64 v[16:17], v[16:17], 2, v[2:3]
	v_mul_hi_u32_u24_e32 v19, s84, v18
	v_mul_u32_u24_e32 v18, s84, v18
	v_lshl_add_u64 v[10:11], v[10:11], 2, v[2:3]
	v_lshl_add_u64 v[12:13], v[12:13], 2, v[2:3]
	v_lshl_add_u64 v[2:3], v[18:19], 2, v[2:3]
	global_load_dword v248, v[4:5], off
	s_nop 0
	global_load_dword v249, v[6:7], off
	s_nop 0
	global_load_dword v250, v[8:9], off
	s_nop 0
	global_load_dword v251, v[10:11], off
	global_load_dword v252, v[12:13], off
	s_nop 0
	global_load_dword v253, v[14:15], off
	s_nop 0
	global_load_dword v176, v[16:17], off
	s_nop 0
	global_load_dword v177, v[2:3], off
	v_add_u32_e32 v2, s85, v80
	v_add_u32_e32 v4, s89, v80
	v_mul_hi_u32_u24_e32 v3, s95, v2
	v_mul_u32_u24_e32 v2, s95, v2
	s_lshl_b32 s38, s88, 1
	v_mul_hi_u32_u24_e32 v5, s95, v4
	v_mul_u32_u24_e32 v4, s95, v4
	v_lshl_add_u64 v[2:3], v[2:3], 1, s[78:79]
	v_mov_b32_e32 v71, v57
	v_lshl_add_u64 v[4:5], v[4:5], 1, s[78:79]
	v_lshl_add_u64 v[2:3], v[2:3], 0, s[38:39]
	s_lshl_b32 s38, s97, 1
	v_add_u32_e32 v17, 0x400, v98
	v_add_u32_e32 v19, 0x4000, v98
	v_add_u32_e32 v20, 0x4200, v98
	v_add_u32_e32 v21, 0x4400, v98
	v_lshl_add_u64 v[10:11], v[2:3], 0, v[70:71]
	v_lshl_add_u64 v[2:3], v[4:5], 0, s[38:39]
	v_add_u32_e32 v22, 0x4600, v98
	v_lshl_add_u64 v[12:13], v[2:3], 0, v[70:71]
	s_lshl_b32 s38, s61, 1
	s_waitcnt vmcnt(31)
	ds_write_b32 v100, v224
	s_waitcnt vmcnt(30)
	ds_write_b32 v100, v225 offset:2080
	s_waitcnt vmcnt(29)
	ds_write_b32 v100, v226 offset:4160
	s_waitcnt vmcnt(28)
	ds_write_b32 v100, v227 offset:6240
	s_waitcnt vmcnt(27)
	ds_write_b32 v100, v228 offset:8320
	s_waitcnt vmcnt(26)
	ds_write_b32 v100, v229 offset:10400
	s_waitcnt vmcnt(25)
	ds_write_b32 v100, v230 offset:12480
	s_waitcnt vmcnt(24)
	ds_write_b32 v100, v231 offset:14560
	s_waitcnt vmcnt(23)
	ds_write_b32 v100, v232 offset:16640
	s_waitcnt vmcnt(22)
	ds_write_b32 v100, v233 offset:18720
	s_waitcnt vmcnt(21)
	ds_write_b32 v100, v234 offset:20800
	s_waitcnt vmcnt(20)
	ds_write_b32 v100, v235 offset:22880
	s_waitcnt vmcnt(19)
	ds_write_b32 v100, v236 offset:24960
	s_waitcnt vmcnt(18)
	ds_write_b32 v100, v237 offset:27040
	s_waitcnt vmcnt(17)
	ds_write_b32 v100, v238 offset:29120
	s_waitcnt vmcnt(16)
	ds_write_b32 v100, v239 offset:31200
	s_waitcnt vmcnt(15)
	ds_write_b32 v100, v240 offset:33280
	s_waitcnt vmcnt(14)
	ds_write_b32 v100, v241 offset:35360
	s_waitcnt vmcnt(13)
	ds_write_b32 v100, v242 offset:37440
	s_waitcnt vmcnt(12)
	ds_write_b32 v100, v243 offset:39520
	s_waitcnt vmcnt(11)
	ds_write_b32 v100, v244 offset:41600
	s_waitcnt vmcnt(10)
	ds_write_b32 v100, v245 offset:43680
	s_waitcnt vmcnt(9)
	ds_write_b32 v100, v246 offset:45760
	s_waitcnt vmcnt(8)
	ds_write_b32 v100, v247 offset:47840
	s_waitcnt vmcnt(7)
	ds_write_b32 v100, v248 offset:49920
	s_waitcnt vmcnt(6)
	ds_write_b32 v100, v249 offset:52000
	s_waitcnt vmcnt(5)
	ds_write_b32 v100, v250 offset:54080
	s_waitcnt vmcnt(4)
	ds_write_b32 v100, v251 offset:56160
	s_waitcnt vmcnt(3)
	ds_write_b32 v100, v252 offset:58240
	s_waitcnt vmcnt(2)
	ds_write_b32 v100, v253 offset:60320
	s_waitcnt vmcnt(1)
	ds_write_b32 v100, v176 offset:62400
	s_waitcnt vmcnt(0)
	ds_write_b32 v100, v177 offset:64480
	s_waitcnt lgkmcnt(0)
	s_barrier
	ds_read2_b32 v[2:3], v98 offset1:65
	ds_read2_b32 v[4:5], v98 offset0:130 offset1:195
	ds_read2_b32 v[6:7], v17 offset0:4 offset1:69
	ds_read2_b32 v[8:9], v17 offset0:134 offset1:199
	ds_read2_b32 v[14:15], v19 offset0:64 offset1:129
	ds_read2_b32 v[16:17], v20 offset0:66 offset1:131
	ds_read2_b32 v[18:19], v21 offset0:68 offset1:133
	ds_read2_b32 v[20:21], v22 offset0:70 offset1:135
	s_waitcnt lgkmcnt(7)
	v_cvt_pk_bf16_f32 v2, v2, v3
	s_waitcnt lgkmcnt(6)
	v_cvt_pk_bf16_f32 v3, v4, v5
	s_waitcnt lgkmcnt(5)
	v_cvt_pk_bf16_f32 v4, v6, v7
	s_waitcnt lgkmcnt(4)
	v_cvt_pk_bf16_f32 v5, v8, v9
	s_waitcnt lgkmcnt(3)
	v_cvt_pk_bf16_f32 v6, v14, v15
	global_store_dwordx4 v[10:11], v[2:5], off
	v_add_u32_e32 v10, 0x8400, v98
	v_add_u32_e32 v14, 0x8800, v98
	v_add_u32_e32 v2, 0x8000, v98
	ds_read2_b32 v[2:3], v2 offset0:128 offset1:193
	ds_read2_b32 v[4:5], v10 offset0:2 offset1:67
	ds_read2_b32 v[10:11], v10 offset0:132 offset1:197
	ds_read2_b32 v[14:15], v14 offset0:6 offset1:71
	s_waitcnt lgkmcnt(6)
	v_cvt_pk_bf16_f32 v7, v16, v17
	s_waitcnt lgkmcnt(5)
	v_cvt_pk_bf16_f32 v8, v18, v19
	s_waitcnt lgkmcnt(4)
	v_cvt_pk_bf16_f32 v9, v20, v21
	global_store_dwordx4 v[12:13], v[6:9], off
	s_waitcnt lgkmcnt(3)
	v_cvt_pk_bf16_f32 v2, v2, v3
	s_waitcnt lgkmcnt(2)
	v_cvt_pk_bf16_f32 v3, v4, v5
	v_add_u32_e32 v6, s60, v80
	v_mul_hi_u32_u24_e32 v7, s95, v6
	v_mul_u32_u24_e32 v6, s95, v6
	v_lshl_add_u64 v[6:7], v[6:7], 1, s[78:79]
	s_waitcnt lgkmcnt(1)
	v_cvt_pk_bf16_f32 v4, v10, v11
	s_waitcnt lgkmcnt(0)
	v_cvt_pk_bf16_f32 v5, v14, v15
	v_lshl_add_u64 v[6:7], v[6:7], 0, s[38:39]
	v_add_u32_e32 v8, 0xc200, v98
	v_add_u32_e32 v10, 0xc400, v98
	v_add_u32_e32 v12, 0xc600, v98
	v_add_u32_e32 v14, 0xc800, v98
	v_lshl_add_u64 v[6:7], v[6:7], 0, v[70:71]
	ds_read2_b32 v[8:9], v8 offset0:64 offset1:129
	ds_read2_b32 v[10:11], v10 offset0:66 offset1:131
	ds_read2_b32 v[12:13], v12 offset0:68 offset1:133
	ds_read2_b32 v[14:15], v14 offset0:70 offset1:135
	global_store_dwordx4 v[6:7], v[2:5], off
	v_add_u32_e32 v6, s14, v80
	v_mul_hi_u32_u24_e32 v7, s95, v6
	v_mul_u32_u24_e32 v6, s95, v6
	v_lshl_add_u64 v[6:7], v[6:7], 1, s[78:79]
	s_lshl_b32 s38, s6, 1
	v_lshl_add_u64 v[6:7], v[6:7], 0, s[38:39]
	s_waitcnt lgkmcnt(3)
	v_cvt_pk_bf16_f32 v2, v8, v9
	s_waitcnt lgkmcnt(2)
	v_cvt_pk_bf16_f32 v3, v10, v11
	s_waitcnt lgkmcnt(1)
	v_cvt_pk_bf16_f32 v4, v12, v13
	s_waitcnt lgkmcnt(0)
	v_cvt_pk_bf16_f32 v5, v14, v15
	v_lshl_add_u64 v[6:7], v[6:7], 0, v[70:71]
	global_store_dwordx4 v[6:7], v[2:5], off
	s_barrier
